# retention sample-state stream: new-state stores write-through sc1 instead of nt (final outputs, never re-read)
# baseline (speedup 1.0000x reference)
; __device__ __forceinline__ void ph_ret_fast(const Params& p, int jl, LAS unsigned char* lds, int tid, int lane, int wave) {
;     ...
; #pragma unroll 8
;             for (int k = 0; k < 64; ++k) { const int d = dq + 4 * k;
;                 const f32x4 sv = __builtin_nontemporal_load((const f32x4*)(sin_ + (size_t)d * RDV));
;                 const f32x4 sn = sv * gamma + v4 * sk[d];
;                 oacc += sn * sq[d];
;                 __builtin_nontemporal_store(sn, (f32x4*)(sout + (size_t)d * RDV)); }
.Lrs_loop:
	global_load_dwordx4 v[212:215], v[22:23], off nt
	v_lshl_add_u64 v[22:23], v[22:23], 0, s[12:13]
	global_load_dwordx4 v[216:219], v[22:23], off nt
	v_lshl_add_u64 v[22:23], v[22:23], 0, s[12:13]
	global_load_dwordx4 v[240:243], v[22:23], off nt
	v_lshl_add_u64 v[22:23], v[22:23], 0, s[12:13]
	global_load_dwordx4 v[244:247], v[22:23], off nt
	v_lshl_add_u64 v[22:23], v[22:23], 0, s[12:13]
	global_load_dwordx4 v[248:251], v[22:23], off nt
	v_lshl_add_u64 v[22:23], v[22:23], 0, s[12:13]
	global_load_dwordx4 v[234:237], v[22:23], off nt
	v_lshl_add_u64 v[22:23], v[22:23], 0, s[12:13]
	global_load_dwordx4 v[90:93], v[22:23], off nt
	v_lshl_add_u64 v[22:23], v[22:23], 0, s[12:13]
	global_load_dwordx4 v[94:97], v[22:23], off nt
	v_lshl_add_u64 v[22:23], v[22:23], 0, s[12:13]
	v_add_u32_e32 v24, 0x400, v35
	ds_read2_b32 v[46:47], v24 offset0:0 offset1:4
	ds_read2_b32 v[48:49], v24 offset0:8 offset1:12
	ds_read2_b32 v[50:51], v24 offset0:16 offset1:20
	ds_read2_b32 v[52:53], v24 offset0:24 offset1:28
	ds_read2_b32 v[36:37], v35 offset0:0 offset1:4
	ds_read2_b32 v[38:39], v35 offset0:8 offset1:12
	ds_read2_b32 v[40:41], v35 offset0:16 offset1:20
	ds_read2_b32 v[42:43], v35 offset0:24 offset1:28
	v_add_u32_e32 v35, 0x80, v35
	s_waitcnt lgkmcnt(0)
	s_waitcnt vmcnt(15)
	v_pk_mul_f32 v[28:29], v[46:47], v[16:17] op_sel_hi:[0,1]
	v_pk_mul_f32 v[44:45], v[46:47], v[14:15] op_sel_hi:[0,1]
	v_pk_fma_f32 v[138:139], v[12:13], v[138:139], v[28:29]
	v_pk_fma_f32 v[136:137], v[18:19], v[136:137], v[44:45]
	v_pk_fma_f32 v[2:3], v[36:37], v[136:137], v[2:3] op_sel_hi:[0,1,1]
	v_pk_fma_f32 v[4:5], v[36:37], v[138:139], v[4:5] op_sel_hi:[0,1,1]
	global_store_dwordx4 v[20:21], v[136:139], off sc1
	v_lshl_add_u64 v[20:21], v[20:21], 0, s[12:13]
	s_waitcnt vmcnt(15)
	v_pk_mul_f32 v[28:29], v[46:47], v[16:17] op_sel:[1,0] op_sel_hi:[1,1]
	v_pk_mul_f32 v[44:45], v[46:47], v[14:15] op_sel:[1,0] op_sel_hi:[1,1]
	v_pk_fma_f32 v[142:143], v[12:13], v[142:143], v[28:29]
	v_pk_fma_f32 v[140:141], v[18:19], v[140:141], v[44:45]
	v_pk_fma_f32 v[2:3], v[36:37], v[140:141], v[2:3] op_sel:[1,0,0] op_sel_hi:[1,1,1]
	v_pk_fma_f32 v[4:5], v[36:37], v[142:143], v[4:5] op_sel:[1,0,0] op_sel_hi:[1,1,1]
	global_store_dwordx4 v[20:21], v[140:143], off sc1
	v_lshl_add_u64 v[20:21], v[20:21], 0, s[12:13]
	s_waitcnt vmcnt(15)
	v_pk_mul_f32 v[28:29], v[48:49], v[16:17] op_sel_hi:[0,1]
	v_pk_mul_f32 v[44:45], v[48:49], v[14:15] op_sel_hi:[0,1]
	v_pk_fma_f32 v[146:147], v[12:13], v[146:147], v[28:29]
	v_pk_fma_f32 v[144:145], v[18:19], v[144:145], v[44:45]
	v_pk_fma_f32 v[2:3], v[38:39], v[144:145], v[2:3] op_sel_hi:[0,1,1]
	v_pk_fma_f32 v[4:5], v[38:39], v[146:147], v[4:5] op_sel_hi:[0,1,1]
	global_store_dwordx4 v[20:21], v[144:147], off sc1
	v_lshl_add_u64 v[20:21], v[20:21], 0, s[12:13]
	s_waitcnt vmcnt(15)
	v_pk_mul_f32 v[28:29], v[48:49], v[16:17] op_sel:[1,0] op_sel_hi:[1,1]
	v_pk_mul_f32 v[44:45], v[48:49], v[14:15] op_sel:[1,0] op_sel_hi:[1,1]
	v_pk_fma_f32 v[150:151], v[12:13], v[150:151], v[28:29]
	v_pk_fma_f32 v[148:149], v[18:19], v[148:149], v[44:45]
	v_pk_fma_f32 v[2:3], v[38:39], v[148:149], v[2:3] op_sel:[1,0,0] op_sel_hi:[1,1,1]
	v_pk_fma_f32 v[4:5], v[38:39], v[150:151], v[4:5] op_sel:[1,0,0] op_sel_hi:[1,1,1]
	global_store_dwordx4 v[20:21], v[148:151], off sc1
	v_lshl_add_u64 v[20:21], v[20:21], 0, s[12:13]
	s_waitcnt vmcnt(15)
	v_pk_mul_f32 v[28:29], v[50:51], v[16:17] op_sel_hi:[0,1]
	v_pk_mul_f32 v[44:45], v[50:51], v[14:15] op_sel_hi:[0,1]
	v_pk_fma_f32 v[154:155], v[12:13], v[154:155], v[28:29]
	v_pk_fma_f32 v[152:153], v[18:19], v[152:153], v[44:45]
	v_pk_fma_f32 v[2:3], v[40:41], v[152:153], v[2:3] op_sel_hi:[0,1,1]
	v_pk_fma_f32 v[4:5], v[40:41], v[154:155], v[4:5] op_sel_hi:[0,1,1]
	global_store_dwordx4 v[20:21], v[152:155], off sc1
	v_lshl_add_u64 v[20:21], v[20:21], 0, s[12:13]
	s_waitcnt vmcnt(15)
	v_pk_mul_f32 v[28:29], v[50:51], v[16:17] op_sel:[1,0] op_sel_hi:[1,1]
	v_pk_mul_f32 v[44:45], v[50:51], v[14:15] op_sel:[1,0] op_sel_hi:[1,1]
	v_pk_fma_f32 v[158:159], v[12:13], v[158:159], v[28:29]
	v_pk_fma_f32 v[156:157], v[18:19], v[156:157], v[44:45]
	v_pk_fma_f32 v[2:3], v[40:41], v[156:157], v[2:3] op_sel:[1,0,0] op_sel_hi:[1,1,1]
	v_pk_fma_f32 v[4:5], v[40:41], v[158:159], v[4:5] op_sel:[1,0,0] op_sel_hi:[1,1,1]
	global_store_dwordx4 v[20:21], v[156:159], off sc1
	v_lshl_add_u64 v[20:21], v[20:21], 0, s[12:13]
	s_waitcnt vmcnt(15)
	v_pk_mul_f32 v[28:29], v[52:53], v[16:17] op_sel_hi:[0,1]
	v_pk_mul_f32 v[44:45], v[52:53], v[14:15] op_sel_hi:[0,1]
	v_pk_fma_f32 v[162:163], v[12:13], v[162:163], v[28:29]
	v_pk_fma_f32 v[160:161], v[18:19], v[160:161], v[44:45]
	v_pk_fma_f32 v[2:3], v[42:43], v[160:161], v[2:3] op_sel_hi:[0,1,1]
	v_pk_fma_f32 v[4:5], v[42:43], v[162:163], v[4:5] op_sel_hi:[0,1,1]
	global_store_dwordx4 v[20:21], v[160:163], off sc1
	v_lshl_add_u64 v[20:21], v[20:21], 0, s[12:13]
	s_waitcnt vmcnt(15)
	v_pk_mul_f32 v[28:29], v[52:53], v[16:17] op_sel:[1,0] op_sel_hi:[1,1]
	v_pk_mul_f32 v[44:45], v[52:53], v[14:15] op_sel:[1,0] op_sel_hi:[1,1]
	v_pk_fma_f32 v[210:211], v[12:13], v[210:211], v[28:29]
	v_pk_fma_f32 v[208:209], v[18:19], v[208:209], v[44:45]
	v_pk_fma_f32 v[2:3], v[42:43], v[208:209], v[2:3] op_sel:[1,0,0] op_sel_hi:[1,1,1]
	v_pk_fma_f32 v[4:5], v[42:43], v[210:211], v[4:5] op_sel:[1,0,0] op_sel_hi:[1,1,1]
	global_store_dwordx4 v[20:21], v[208:211], off sc1
	v_lshl_add_u64 v[20:21], v[20:21], 0, s[12:13]
	s_cmp_eq_u32 s2, 3
	s_cbranch_scc1 .Lrs_skipa
	global_load_dwordx4 v[136:139], v[22:23], off nt
	v_lshl_add_u64 v[22:23], v[22:23], 0, s[12:13]
	global_load_dwordx4 v[140:143], v[22:23], off nt
	v_lshl_add_u64 v[22:23], v[22:23], 0, s[12:13]
	global_load_dwordx4 v[144:147], v[22:23], off nt
	v_lshl_add_u64 v[22:23], v[22:23], 0, s[12:13]
	global_load_dwordx4 v[148:151], v[22:23], off nt
	v_lshl_add_u64 v[22:23], v[22:23], 0, s[12:13]
	global_load_dwordx4 v[152:155], v[22:23], off nt
	v_lshl_add_u64 v[22:23], v[22:23], 0, s[12:13]
	global_load_dwordx4 v[156:159], v[22:23], off nt
	v_lshl_add_u64 v[22:23], v[22:23], 0, s[12:13]
	global_load_dwordx4 v[160:163], v[22:23], off nt
	v_lshl_add_u64 v[22:23], v[22:23], 0, s[12:13]
	global_load_dwordx4 v[208:211], v[22:23], off nt
	v_lshl_add_u64 v[22:23], v[22:23], 0, s[12:13]
; #define LAS __attribute__((address_space(3)))
; __device__ __forceinline__ void st_bf4(bf16* q, const f32x4 v) { v2u w; w.x = cvt_pk_bf16(v.x, v.y); w.y = cvt_pk_bf16(v.z, v.w); *(v2u*)q = w; }
; __device__ __forceinline__ void ph_ret_fast(const Params& p, int jl, LAS unsigned char* lds, int tid, int lane, int wave) {
;     ...
; #pragma unroll 8
;             for (int k = 0; k < 64; ++k) { const int d = dq + 4 * k;
;                 const f32x4 sv = __builtin_nontemporal_load((const f32x4*)(sin_ + (size_t)d * RDV));
;                 const f32x4 sn = sv * gamma + v4 * sk[d];
;                 oacc += sn * sq[d];
;                 __builtin_nontemporal_store(sn, (f32x4*)(sout + (size_t)d * RDV)); }
;             *(LAS f32x4*)(red + dq * 512 + 4 * e4) = oacc;
;             __syncthreads();
;             if (dq == 0) { const f32x4 r = (*(LAS f32x4*)(red + 4 * e4) + *(LAS f32x4*)(red + 512 + 4 * e4)) + (*(LAS f32x4*)(red + 1024 + 4 * e4) + *(LAS f32x4*)(red + 1536 + 4 * e4));
;                 st_bf4(O + (size_t)row * RV + 512 * h + 4 * e4, r); }
.Lrs_skipa:
	v_add_u32_e32 v24, 0x400, v35
	ds_read2_b32 v[46:47], v24 offset0:0 offset1:4
	ds_read2_b32 v[48:49], v24 offset0:8 offset1:12
	ds_read2_b32 v[50:51], v24 offset0:16 offset1:20
	ds_read2_b32 v[52:53], v24 offset0:24 offset1:28
	ds_read2_b32 v[36:37], v35 offset0:0 offset1:4
	ds_read2_b32 v[38:39], v35 offset0:8 offset1:12
	ds_read2_b32 v[40:41], v35 offset0:16 offset1:20
	ds_read2_b32 v[42:43], v35 offset0:24 offset1:28
	v_add_u32_e32 v35, 0x80, v35
	s_waitcnt lgkmcnt(0)
	s_waitcnt vmcnt(15)
	v_pk_mul_f32 v[28:29], v[46:47], v[16:17] op_sel_hi:[0,1]
	v_pk_mul_f32 v[44:45], v[46:47], v[14:15] op_sel_hi:[0,1]
	v_pk_fma_f32 v[214:215], v[12:13], v[214:215], v[28:29]
	v_pk_fma_f32 v[212:213], v[18:19], v[212:213], v[44:45]
	v_pk_fma_f32 v[2:3], v[36:37], v[212:213], v[2:3] op_sel_hi:[0,1,1]
	v_pk_fma_f32 v[4:5], v[36:37], v[214:215], v[4:5] op_sel_hi:[0,1,1]
	global_store_dwordx4 v[20:21], v[212:215], off sc1
	v_lshl_add_u64 v[20:21], v[20:21], 0, s[12:13]
	s_waitcnt vmcnt(15)
	v_pk_mul_f32 v[28:29], v[46:47], v[16:17] op_sel:[1,0] op_sel_hi:[1,1]
	v_pk_mul_f32 v[44:45], v[46:47], v[14:15] op_sel:[1,0] op_sel_hi:[1,1]
	v_pk_fma_f32 v[218:219], v[12:13], v[218:219], v[28:29]
	v_pk_fma_f32 v[216:217], v[18:19], v[216:217], v[44:45]
	v_pk_fma_f32 v[2:3], v[36:37], v[216:217], v[2:3] op_sel:[1,0,0] op_sel_hi:[1,1,1]
	v_pk_fma_f32 v[4:5], v[36:37], v[218:219], v[4:5] op_sel:[1,0,0] op_sel_hi:[1,1,1]
	global_store_dwordx4 v[20:21], v[216:219], off sc1
	v_lshl_add_u64 v[20:21], v[20:21], 0, s[12:13]
	s_waitcnt vmcnt(15)
	v_pk_mul_f32 v[28:29], v[48:49], v[16:17] op_sel_hi:[0,1]
	v_pk_mul_f32 v[44:45], v[48:49], v[14:15] op_sel_hi:[0,1]
	v_pk_fma_f32 v[242:243], v[12:13], v[242:243], v[28:29]
	v_pk_fma_f32 v[240:241], v[18:19], v[240:241], v[44:45]
	v_pk_fma_f32 v[2:3], v[38:39], v[240:241], v[2:3] op_sel_hi:[0,1,1]
	v_pk_fma_f32 v[4:5], v[38:39], v[242:243], v[4:5] op_sel_hi:[0,1,1]
	global_store_dwordx4 v[20:21], v[240:243], off sc1
	v_lshl_add_u64 v[20:21], v[20:21], 0, s[12:13]
	s_waitcnt vmcnt(15)
	v_pk_mul_f32 v[28:29], v[48:49], v[16:17] op_sel:[1,0] op_sel_hi:[1,1]
	v_pk_mul_f32 v[44:45], v[48:49], v[14:15] op_sel:[1,0] op_sel_hi:[1,1]
	v_pk_fma_f32 v[246:247], v[12:13], v[246:247], v[28:29]
	v_pk_fma_f32 v[244:245], v[18:19], v[244:245], v[44:45]
	v_pk_fma_f32 v[2:3], v[38:39], v[244:245], v[2:3] op_sel:[1,0,0] op_sel_hi:[1,1,1]
	v_pk_fma_f32 v[4:5], v[38:39], v[246:247], v[4:5] op_sel:[1,0,0] op_sel_hi:[1,1,1]
	global_store_dwordx4 v[20:21], v[244:247], off sc1
	v_lshl_add_u64 v[20:21], v[20:21], 0, s[12:13]
	s_waitcnt vmcnt(15)
	v_pk_mul_f32 v[28:29], v[50:51], v[16:17] op_sel_hi:[0,1]
	v_pk_mul_f32 v[44:45], v[50:51], v[14:15] op_sel_hi:[0,1]
	v_pk_fma_f32 v[250:251], v[12:13], v[250:251], v[28:29]
	v_pk_fma_f32 v[248:249], v[18:19], v[248:249], v[44:45]
	v_pk_fma_f32 v[2:3], v[40:41], v[248:249], v[2:3] op_sel_hi:[0,1,1]
	v_pk_fma_f32 v[4:5], v[40:41], v[250:251], v[4:5] op_sel_hi:[0,1,1]
	global_store_dwordx4 v[20:21], v[248:251], off sc1
	v_lshl_add_u64 v[20:21], v[20:21], 0, s[12:13]
	s_waitcnt vmcnt(15)
	v_pk_mul_f32 v[28:29], v[50:51], v[16:17] op_sel:[1,0] op_sel_hi:[1,1]
	v_pk_mul_f32 v[44:45], v[50:51], v[14:15] op_sel:[1,0] op_sel_hi:[1,1]
	v_pk_fma_f32 v[236:237], v[12:13], v[236:237], v[28:29]
	v_pk_fma_f32 v[234:235], v[18:19], v[234:235], v[44:45]
	v_pk_fma_f32 v[2:3], v[40:41], v[234:235], v[2:3] op_sel:[1,0,0] op_sel_hi:[1,1,1]
	v_pk_fma_f32 v[4:5], v[40:41], v[236:237], v[4:5] op_sel:[1,0,0] op_sel_hi:[1,1,1]
	global_store_dwordx4 v[20:21], v[234:237], off sc1
	v_lshl_add_u64 v[20:21], v[20:21], 0, s[12:13]
	s_waitcnt vmcnt(15)
	v_pk_mul_f32 v[28:29], v[52:53], v[16:17] op_sel_hi:[0,1]
	v_pk_mul_f32 v[44:45], v[52:53], v[14:15] op_sel_hi:[0,1]
	v_pk_fma_f32 v[92:93], v[12:13], v[92:93], v[28:29]
	v_pk_fma_f32 v[90:91], v[18:19], v[90:91], v[44:45]
	v_pk_fma_f32 v[2:3], v[42:43], v[90:91], v[2:3] op_sel_hi:[0,1,1]
	v_pk_fma_f32 v[4:5], v[42:43], v[92:93], v[4:5] op_sel_hi:[0,1,1]
	global_store_dwordx4 v[20:21], v[90:93], off sc1
	v_lshl_add_u64 v[20:21], v[20:21], 0, s[12:13]
	s_waitcnt vmcnt(15)
	v_pk_mul_f32 v[28:29], v[52:53], v[16:17] op_sel:[1,0] op_sel_hi:[1,1]
	v_pk_mul_f32 v[44:45], v[52:53], v[14:15] op_sel:[1,0] op_sel_hi:[1,1]
	v_pk_fma_f32 v[96:97], v[12:13], v[96:97], v[28:29]
	v_pk_fma_f32 v[94:95], v[18:19], v[94:95], v[44:45]
	v_pk_fma_f32 v[2:3], v[42:43], v[94:95], v[2:3] op_sel:[1,0,0] op_sel_hi:[1,1,1]
	v_pk_fma_f32 v[4:5], v[42:43], v[96:97], v[4:5] op_sel:[1,0,0] op_sel_hi:[1,1,1]
	global_store_dwordx4 v[20:21], v[94:97], off sc1
	v_lshl_add_u64 v[20:21], v[20:21], 0, s[12:13]
	s_add_i32 s2, s2, 1
	s_cmp_eq_u32 s2, 4
	s_cbranch_scc0 .Lrs_loop
	ds_write_b128 v32, v[2:5] offset:2048
	s_waitcnt lgkmcnt(0)
	s_barrier
	s_and_saveexec_b64 s[2:3], s[6:7]
	s_cbranch_execz .LBB0_459
	ds_read_b128 v[2:5], v31 offset:2048
	ds_read_b128 v[12:15], v31 offset:4096
	s_lshl_b64 s[0:1], s[0:1], 1
	v_readlane_b32 s10, v252, 54
	v_readlane_b32 s11, v252, 55
	s_add_u32 s0, s10, s0
	s_waitcnt lgkmcnt(0)
	v_pk_add_f32 v[16:17], v[4:5], v[14:15]
	v_pk_add_f32 v[18:19], v[2:3], v[12:13]
	ds_read_b128 v[2:5], v31 offset:6144
	ds_read_b128 v[12:15], v31 offset:8192
	s_addc_u32 s1, s11, s1
	s_lshl_b32 s9, s9, 1
	s_add_u32 s0, s0, s9
	s_addc_u32 s1, s1, 0
	s_waitcnt lgkmcnt(0)
	v_pk_add_f32 v[2:3], v[2:3], v[12:13]
	v_pk_add_f32 v[4:5], v[4:5], v[14:15]
	v_pk_add_f32 v[2:3], v[18:19], v[2:3]
	v_pk_add_f32 v[4:5], v[16:17], v[4:5]
	v_cvt_pk_bf16_f32 v2, v2, v3
	s_nop 0
	v_cvt_pk_bf16_f32 v3, v4, v5
	global_store_dwordx2 v34, v[2:3], s[0:1]
	s_branch .LBB0_459
